# v49 + gate/up: next tile's first two LDS-DMA loads issued at the epilogue head (ahead of the stores); first tile keeps plain peeled body
# baseline (speedup 1.0000x reference)
; #define PG8_STAGE(bufoff, gbase, voff) do { _Pragma("unroll") for (int _i = 0; _i < 2; ++_i) \
;         __builtin_amdgcn_global_load_lds((const unsigned*)((const char*)(gbase) + (voff)[_i]), (PG8_LAS unsigned*)(lds + (bufoff) + ldsw + _i * 8192), 16, 0, 0); } while (0)
; #define PG8_LDA(dst, b, h) do { _Pragma("unroll") for (int m = 0; m < 4; ++m) _Pragma("unroll") for (int k = 0; k < 2; ++k) dst[m][k] = *(const PG8_LAS bf16x8*)(lds + PG8_SA(b, h) + aoff + m * 2048 + k * 1024); } while (0)
; #define PG8_LDB(dst, b, h) do { _Pragma("unroll") for (int n = 0; n < 2; ++n) _Pragma("unroll") for (int k = 0; k < 2; ++k) dst[n][k] = *(const PG8_LAS bf16x8*)(lds + PG8_SB(b, h) + boff + n * 2048 + k * 1024); } while (0)
; #define PG8_MMA(ai, bj, At, Bt) do { __builtin_amdgcn_s_setprio(1); _Pragma("unroll") for (int m = 0; m < 4; ++m) _Pragma("unroll") for (int n = 0; n < 2; ++n) _Pragma("unroll") for (int k = 0; k < 2; ++k) \
;         acc[ai][bj][m][n] = mma16<F16>(Bt[n][k], At[m][k], acc[ai][bj][m][n]); __builtin_amdgcn_s_setprio(0); } while (0)
; #define PG8_WAIT_V(n) asm volatile("s_waitcnt vmcnt(" #n ")" ::: "memory")
; #define PG8_WAIT_L(n) asm volatile("s_waitcnt lgkmcnt(" #n ")" ::: "memory")
; #define PG8_BAR __builtin_amdgcn_s_barrier()
; #define PG8_SCHED __builtin_amdgcn_sched_barrier(0)
; template <class Epi, class Sched, bool ALIGN_EPI = false, bool SP2 = false, bool F16 = false>
; __device__ __forceinline__ void gemm_phase(PG8_LAS unsigned char* lds, const Gemm g, const Sched& S, const Epi& E) {
;     ...
;             PG8_LDB(B0, 0, 0); PG8_LDB(B1, 0, 1); PG8_SCHED; PG8_LDA(At, 0, 0); PG8_STAGE(PG8_SA(1, 1), a1 + hstep, voffA);
;             PG8_WAIT_V(8); PG8_WAIT_L(0); PG8_BAR; PG8_MMA(0, 0, At, B0); PG8_MMA(0, 1, At, B1); PG8_BAR; PG8_SCHED;
;             PG8_LDA(At, 0, 1); PG8_STAGE(PG8_SB(0, 0), b2, voffB); PG8_STAGE(PG8_SB(0, 1), b2 + hstep, voffB); PG8_STAGE(PG8_SA(0, 0), a2, voffA);
;             PG8_WAIT_V(8); PG8_WAIT_L(0); PG8_BAR; PG8_MMA(1, 0, At, B0); PG8_MMA(1, 1, At, B1); PG8_BAR; PG8_SCHED;
.Lgu_first:
	s_add_u32 s56, s54, 0xfffc0080
	s_addc_u32 s57, s55, -1
	s_add_i32 s62, 0, 0x10000
	s_cmp_eq_u32 s61, 12
	s_cselect_b32 s59, s4, s57
	s_cselect_b32 s58, s5, s56
	s_cselect_b32 s57, s37, s60
	s_cselect_b32 s56, s47, s49
	s_add_i32 s64, 0, 0x14000
	ds_read_b128 v[32:35], v172
	ds_read_b128 v[36:39], v172 offset:1024
	ds_read_b128 v[40:43], v172 offset:2048
	ds_read_b128 v[44:47], v172 offset:3072
	ds_read_b128 v[156:159], v172 offset:16384
	ds_read_b128 v[168:171], v172 offset:17408
	ds_read_b128 v[186:189], v172 offset:18432
	ds_read_b128 v[190:193], v172 offset:19456
	s_add_i32 m0, s9, 0xc000
	ds_read_b128 v[194:197], v165
	ds_read_b128 v[198:201], v165 offset:1024
	ds_read_b128 v[202:205], v165 offset:2048
	ds_read_b128 v[206:209], v165 offset:3072
	ds_read_b128 v[210:213], v165 offset:4096
	ds_read_b128 v[214:217], v165 offset:5120
	ds_read_b128 v[218:221], v165 offset:6144
	ds_read_b128 v[222:225], v165 offset:7168
	global_load_lds_dwordx4 v152, s[54:55]
	s_add_i32 m0, s9, 0xe000
	s_nop 0
	global_load_lds_dwordx4 v154, s[54:55]
	s_waitcnt vmcnt(8)
	s_waitcnt lgkmcnt(0)
	s_barrier
	s_setprio 1
	s_waitcnt lgkmcnt(0)
	v_mfma_f32_16x16x32_f16 v[142:145], v[32:35], v[194:197], 0
	v_mfma_f32_16x16x32_f16 v[138:141], v[40:43], v[194:197], 0
	v_mfma_f32_16x16x32_f16 v[124:127], v[32:35], v[202:205], 0
	v_mfma_f32_16x16x32_f16 v[120:123], v[40:43], v[202:205], 0
	v_mfma_f32_16x16x32_f16 v[108:111], v[32:35], v[210:213], 0
	v_mfma_f32_16x16x32_f16 v[104:107], v[40:43], v[210:213], 0
	v_mfma_f32_16x16x32_f16 v[92:95], v[32:35], v[218:221], 0
	v_mfma_f32_16x16x32_f16 v[88:91], v[40:43], v[218:221], 0
	v_mfma_f32_16x16x32_f16 v[142:145], v[36:39], v[198:201], v[142:145]
	v_mfma_f32_16x16x32_f16 v[138:141], v[44:47], v[198:201], v[138:141]
	v_mfma_f32_16x16x32_f16 v[124:127], v[36:39], v[206:209], v[124:127]
	v_mfma_f32_16x16x32_f16 v[120:123], v[44:47], v[206:209], v[120:123]
	v_mfma_f32_16x16x32_f16 v[108:111], v[36:39], v[214:217], v[108:111]
	v_mfma_f32_16x16x32_f16 v[104:107], v[44:47], v[214:217], v[104:107]
	v_mfma_f32_16x16x32_f16 v[92:95], v[36:39], v[222:225], v[92:95]
	v_mfma_f32_16x16x32_f16 v[88:91], v[44:47], v[222:225], v[88:91]
	v_mfma_f32_16x16x32_f16 v[134:137], v[156:159], v[194:197], 0
	v_mfma_f32_16x16x32_f16 v[130:133], v[186:189], v[194:197], 0
	v_mfma_f32_16x16x32_f16 v[116:119], v[156:159], v[202:205], 0
	v_mfma_f32_16x16x32_f16 v[112:115], v[186:189], v[202:205], 0
	v_mfma_f32_16x16x32_f16 v[100:103], v[156:159], v[210:213], 0
	v_mfma_f32_16x16x32_f16 v[96:99], v[186:189], v[210:213], 0
	v_mfma_f32_16x16x32_f16 v[84:87], v[156:159], v[218:221], 0
	v_mfma_f32_16x16x32_f16 v[80:83], v[186:189], v[218:221], 0
	v_mfma_f32_16x16x32_f16 v[134:137], v[168:171], v[198:201], v[134:137]
	v_mfma_f32_16x16x32_f16 v[130:133], v[190:193], v[198:201], v[130:133]
	v_mfma_f32_16x16x32_f16 v[116:119], v[168:171], v[206:209], v[116:119]
	v_mfma_f32_16x16x32_f16 v[112:115], v[190:193], v[206:209], v[112:115]
	v_mfma_f32_16x16x32_f16 v[100:103], v[168:171], v[214:217], v[100:103]
	v_mfma_f32_16x16x32_f16 v[96:99], v[190:193], v[214:217], v[96:99]
	v_mfma_f32_16x16x32_f16 v[84:87], v[168:171], v[222:225], v[84:87]
	v_mfma_f32_16x16x32_f16 v[80:83], v[190:193], v[222:225], v[80:83]
	s_setprio 0
	s_barrier
	s_add_u32 s98, s56, s16
	s_addc_u32 s99, s57, s17
	s_add_u32 s100, s58, s16
	s_addc_u32 s101, s59, s17
	s_add_i32 s62, s62, s8
	s_mov_b32 m0, s62
	ds_read_b128 v[194:197], v165 offset:16384
	ds_read_b128 v[198:201], v165 offset:17408
	ds_read_b128 v[202:205], v165 offset:18432
	ds_read_b128 v[206:209], v165 offset:19456
	ds_read_b128 v[210:213], v165 offset:20480
	ds_read_b128 v[214:217], v165 offset:21504
	ds_read_b128 v[218:221], v165 offset:22528
	ds_read_b128 v[222:225], v165 offset:23552
	global_load_lds_dwordx4 v128, s[56:57]
	s_add_i32 m0, s62, 0x2000
	s_add_u32 s62, s56, 0x40000
	s_addc_u32 s63, s57, 0
	s_add_i32 s64, s64, s8
	global_load_lds_dwordx4 v146, s[56:57]
	s_mov_b32 m0, s64
	s_nop 0
	global_load_lds_dwordx4 v128, s[62:63]
	s_add_i32 m0, s64, 0x2000
	s_nop 0
	global_load_lds_dwordx4 v146, s[62:63]
	s_mov_b32 m0, s9
	s_nop 0
	global_load_lds_dwordx4 v150, s[58:59]
	s_mov_b32 m0, s10
	s_nop 0
	global_load_lds_dwordx4 v148, s[58:59]
	s_waitcnt vmcnt(8)
	s_waitcnt lgkmcnt(0)
	s_barrier
	s_setprio 1
	s_waitcnt lgkmcnt(0)
	v_mfma_f32_16x16x32_f16 v[76:79], v[32:35], v[194:197], 0
	v_mfma_f32_16x16x32_f16 v[72:75], v[40:43], v[194:197], 0
	v_mfma_f32_16x16x32_f16 v[60:63], v[32:35], v[202:205], 0
	v_mfma_f32_16x16x32_f16 v[56:59], v[40:43], v[202:205], 0
	v_mfma_f32_16x16x32_f16 v[28:31], v[32:35], v[210:213], 0
	v_mfma_f32_16x16x32_f16 v[24:27], v[40:43], v[210:213], 0
	v_mfma_f32_16x16x32_f16 v[12:15], v[32:35], v[218:221], 0
	v_mfma_f32_16x16x32_f16 v[8:11], v[40:43], v[218:221], 0
	v_mfma_f32_16x16x32_f16 v[76:79], v[36:39], v[198:201], v[76:79]
	v_mfma_f32_16x16x32_f16 v[72:75], v[44:47], v[198:201], v[72:75]
	v_mfma_f32_16x16x32_f16 v[60:63], v[36:39], v[206:209], v[60:63]
	v_mfma_f32_16x16x32_f16 v[56:59], v[44:47], v[206:209], v[56:59]
	v_mfma_f32_16x16x32_f16 v[28:31], v[36:39], v[214:217], v[28:31]
	v_mfma_f32_16x16x32_f16 v[24:27], v[44:47], v[214:217], v[24:27]
	v_mfma_f32_16x16x32_f16 v[12:15], v[36:39], v[222:225], v[12:15]
	v_mfma_f32_16x16x32_f16 v[8:11], v[44:47], v[222:225], v[8:11]
	v_mfma_f32_16x16x32_f16 v[20:23], v[156:159], v[210:213], 0
	v_mfma_f32_16x16x32_f16 v[16:19], v[186:189], v[210:213], 0
	v_mfma_f32_16x16x32_f16 v[4:7], v[156:159], v[218:221], 0
	v_mfma_f32_16x16x32_f16 v[0:3], v[186:189], v[218:221], 0
	v_mfma_f32_16x16x32_f16 v[32:35], v[156:159], v[194:197], 0
	v_mfma_f32_16x16x32_f16 v[36:39], v[186:189], v[194:197], 0
	v_mfma_f32_16x16x32_f16 v[40:43], v[156:159], v[202:205], 0
	v_mfma_f32_16x16x32_f16 v[44:47], v[186:189], v[202:205], 0
	v_mfma_f32_16x16x32_f16 v[20:23], v[168:171], v[214:217], v[20:23]
	v_mfma_f32_16x16x32_f16 v[16:19], v[190:193], v[214:217], v[16:19]
	v_mfma_f32_16x16x32_f16 v[4:7], v[168:171], v[222:225], v[4:7]
	v_mfma_f32_16x16x32_f16 v[0:3], v[190:193], v[222:225], v[0:3]
	v_mfma_f32_16x16x32_f16 v[32:35], v[168:171], v[198:201], v[32:35]
	v_mfma_f32_16x16x32_f16 v[36:39], v[190:193], v[198:201], v[36:39]
	v_mfma_f32_16x16x32_f16 v[40:43], v[168:171], v[206:209], v[40:43]
	v_mfma_f32_16x16x32_f16 v[44:47], v[190:193], v[206:209], v[44:47]
	s_setprio 0
	s_barrier
; #define PG8_STAGE(bufoff, gbase, voff) do { _Pragma("unroll") for (int _i = 0; _i < 2; ++_i) \
;         __builtin_amdgcn_global_load_lds((const unsigned*)((const char*)(gbase) + (voff)[_i]), (PG8_LAS unsigned*)(lds + (bufoff) + ldsw + _i * 8192), 16, 0, 0); } while (0)
; #define PG8_LDA(dst, b, h) do { _Pragma("unroll") for (int m = 0; m < 4; ++m) _Pragma("unroll") for (int k = 0; k < 2; ++k) dst[m][k] = *(const PG8_LAS bf16x8*)(lds + PG8_SA(b, h) + aoff + m * 2048 + k * 1024); } while (0)
; #define PG8_LDB(dst, b, h) do { _Pragma("unroll") for (int n = 0; n < 2; ++n) _Pragma("unroll") for (int k = 0; k < 2; ++k) dst[n][k] = *(const PG8_LAS bf16x8*)(lds + PG8_SB(b, h) + boff + n * 2048 + k * 1024); } while (0)
; #define PG8_MMA(ai, bj, At, Bt) do { __builtin_amdgcn_s_setprio(1); _Pragma("unroll") for (int m = 0; m < 4; ++m) _Pragma("unroll") for (int n = 0; n < 2; ++n) _Pragma("unroll") for (int k = 0; k < 2; ++k) \
;         acc[ai][bj][m][n] = mma16<F16>(Bt[n][k], At[m][k], acc[ai][bj][m][n]); __builtin_amdgcn_s_setprio(0); } while (0)
; #define PG8_WAIT_V(n) asm volatile("s_waitcnt vmcnt(" #n ")" ::: "memory")
; #define PG8_WAIT_L(n) asm volatile("s_waitcnt lgkmcnt(" #n ")" ::: "memory")
; #define PG8_BAR __builtin_amdgcn_s_barrier()
; #define PG8_SCHED __builtin_amdgcn_sched_barrier(0)
; template <class Epi, class Sched, bool ALIGN_EPI = false, bool SP2 = false, bool F16 = false>
; __device__ __forceinline__ void gemm_phase(PG8_LAS unsigned char* lds, const Gemm g, const Sched& S, const Epi& E) {
;     ...
;             PG8_LDB(B0, 1, 0); PG8_LDB(B1, 1, 1); PG8_SCHED; PG8_LDA(At, 1, 0); PG8_STAGE(PG8_SA(0, 1), a2 + hstep, voffA);
;             PG8_WAIT_V(8); PG8_WAIT_L(0); PG8_BAR; PG8_MMA(0, 0, At, B0); PG8_MMA(0, 1, At, B1); PG8_BAR; PG8_SCHED;
;             PG8_LDA(At, 1, 1); PG8_STAGE(PG8_SB(1, 0), b3, voffB); PG8_STAGE(PG8_SB(1, 1), b3 + hstep, voffB); PG8_STAGE(PG8_SA(1, 0), a3, voffA);
;             PG8_WAIT_V(8); PG8_WAIT_L(0); PG8_BAR; PG8_MMA(1, 0, At, B0); PG8_MMA(1, 1, At, B1); PG8_BAR; PG8_SCHED;
	s_add_i32 s62, 0, 0x18000
	s_add_i32 s63, 0, 0x1c000
	ds_read_b128 v[48:51], v172 offset:32768
	ds_read_b128 v[52:55], v172 offset:33792
	ds_read_b128 v[64:67], v172 offset:34816
	ds_read_b128 v[68:71], v172 offset:35840
	ds_read_b128 v[156:159], v172 offset:49152
	ds_read_b128 v[168:171], v172 offset:50176
	ds_read_b128 v[186:189], v172 offset:51200
	ds_read_b128 v[190:193], v172 offset:52224
	s_add_u32 s58, s58, 0x40000
	s_addc_u32 s59, s59, 0
	s_mov_b32 m0, s11
	ds_read_b128 v[194:197], v165 offset:32768
	ds_read_b128 v[198:201], v165 offset:33792
	ds_read_b128 v[202:205], v165 offset:34816
	ds_read_b128 v[206:209], v165 offset:35840
	ds_read_b128 v[210:213], v165 offset:36864
	ds_read_b128 v[214:217], v165 offset:37888
	ds_read_b128 v[218:221], v165 offset:38912
	ds_read_b128 v[222:225], v165 offset:39936
	global_load_lds_dwordx4 v150, s[58:59]
	s_mov_b32 m0, s13
	s_nop 0
	global_load_lds_dwordx4 v148, s[58:59]
	s_waitcnt vmcnt(8)
	s_waitcnt lgkmcnt(0)
	s_barrier
	s_setprio 1
	s_waitcnt lgkmcnt(0)
	v_mfma_f32_16x16x32_f16 v[142:145], v[48:51], v[194:197], v[142:145]
	v_mfma_f32_16x16x32_f16 v[138:141], v[64:67], v[194:197], v[138:141]
	v_mfma_f32_16x16x32_f16 v[124:127], v[48:51], v[202:205], v[124:127]
	v_mfma_f32_16x16x32_f16 v[120:123], v[64:67], v[202:205], v[120:123]
	v_mfma_f32_16x16x32_f16 v[108:111], v[48:51], v[210:213], v[108:111]
	v_mfma_f32_16x16x32_f16 v[104:107], v[64:67], v[210:213], v[104:107]
	v_mfma_f32_16x16x32_f16 v[92:95], v[48:51], v[218:221], v[92:95]
	v_mfma_f32_16x16x32_f16 v[88:91], v[64:67], v[218:221], v[88:91]
	v_mfma_f32_16x16x32_f16 v[142:145], v[52:55], v[198:201], v[142:145]
	v_mfma_f32_16x16x32_f16 v[138:141], v[68:71], v[198:201], v[138:141]
	v_mfma_f32_16x16x32_f16 v[124:127], v[52:55], v[206:209], v[124:127]
	v_mfma_f32_16x16x32_f16 v[120:123], v[68:71], v[206:209], v[120:123]
	v_mfma_f32_16x16x32_f16 v[108:111], v[52:55], v[214:217], v[108:111]
	v_mfma_f32_16x16x32_f16 v[104:107], v[68:71], v[214:217], v[104:107]
	v_mfma_f32_16x16x32_f16 v[92:95], v[52:55], v[222:225], v[92:95]
	v_mfma_f32_16x16x32_f16 v[88:91], v[68:71], v[222:225], v[88:91]
	v_mfma_f32_16x16x32_f16 v[134:137], v[156:159], v[194:197], v[134:137]
	v_mfma_f32_16x16x32_f16 v[130:133], v[186:189], v[194:197], v[130:133]
	v_mfma_f32_16x16x32_f16 v[116:119], v[156:159], v[202:205], v[116:119]
	v_mfma_f32_16x16x32_f16 v[112:115], v[186:189], v[202:205], v[112:115]
	v_mfma_f32_16x16x32_f16 v[100:103], v[156:159], v[210:213], v[100:103]
	v_mfma_f32_16x16x32_f16 v[96:99], v[186:189], v[210:213], v[96:99]
	v_mfma_f32_16x16x32_f16 v[84:87], v[156:159], v[218:221], v[84:87]
	v_mfma_f32_16x16x32_f16 v[80:83], v[186:189], v[218:221], v[80:83]
	v_mfma_f32_16x16x32_f16 v[134:137], v[168:171], v[198:201], v[134:137]
	v_mfma_f32_16x16x32_f16 v[130:133], v[190:193], v[198:201], v[130:133]
	v_mfma_f32_16x16x32_f16 v[116:119], v[168:171], v[206:209], v[116:119]
	v_mfma_f32_16x16x32_f16 v[112:115], v[190:193], v[206:209], v[112:115]
	v_mfma_f32_16x16x32_f16 v[100:103], v[168:171], v[214:217], v[100:103]
	v_mfma_f32_16x16x32_f16 v[96:99], v[190:193], v[214:217], v[96:99]
	v_mfma_f32_16x16x32_f16 v[84:87], v[168:171], v[222:225], v[84:87]
	v_mfma_f32_16x16x32_f16 v[80:83], v[190:193], v[222:225], v[80:83]
	s_setprio 0
	s_barrier
	s_add_i32 s58, s62, s8
	s_mov_b32 m0, s58
	ds_read_b128 v[194:197], v165 offset:49152
	ds_read_b128 v[198:201], v165 offset:50176
	ds_read_b128 v[202:205], v165 offset:51200
	ds_read_b128 v[206:209], v165 offset:52224
	ds_read_b128 v[210:213], v165 offset:53248
	ds_read_b128 v[214:217], v165 offset:54272
	ds_read_b128 v[218:221], v165 offset:55296
	ds_read_b128 v[222:225], v165 offset:56320
	global_load_lds_dwordx4 v128, s[98:99]
	s_add_i32 m0, s58, 0x2000
	s_add_u32 s56, s56, 0x40080
	s_addc_u32 s57, s57, 0
	s_add_i32 s58, s63, s8
	global_load_lds_dwordx4 v146, s[98:99]
	s_mov_b32 m0, s58
	s_nop 0
	global_load_lds_dwordx4 v128, s[56:57]
	s_add_i32 m0, s58, 0x2000
	s_nop 0
	global_load_lds_dwordx4 v146, s[56:57]
	s_mov_b32 m0, s20
	s_nop 0
	global_load_lds_dwordx4 v150, s[100:101]
	s_mov_b32 m0, s21
	s_nop 0
	global_load_lds_dwordx4 v148, s[100:101]
	s_waitcnt vmcnt(8)
	s_waitcnt lgkmcnt(0)
	s_barrier
	s_setprio 1
	s_waitcnt lgkmcnt(0)
	v_mfma_f32_16x16x32_f16 v[76:79], v[48:51], v[194:197], v[76:79]
	v_mfma_f32_16x16x32_f16 v[72:75], v[64:67], v[194:197], v[72:75]
	v_mfma_f32_16x16x32_f16 v[60:63], v[48:51], v[202:205], v[60:63]
	v_mfma_f32_16x16x32_f16 v[56:59], v[64:67], v[202:205], v[56:59]
	v_mfma_f32_16x16x32_f16 v[28:31], v[48:51], v[210:213], v[28:31]
	v_mfma_f32_16x16x32_f16 v[24:27], v[64:67], v[210:213], v[24:27]
	v_mfma_f32_16x16x32_f16 v[12:15], v[48:51], v[218:221], v[12:15]
	v_mfma_f32_16x16x32_f16 v[8:11], v[64:67], v[218:221], v[8:11]
	v_mfma_f32_16x16x32_f16 v[76:79], v[52:55], v[198:201], v[76:79]
	v_mfma_f32_16x16x32_f16 v[72:75], v[68:71], v[198:201], v[72:75]
	v_mfma_f32_16x16x32_f16 v[60:63], v[52:55], v[206:209], v[60:63]
	v_mfma_f32_16x16x32_f16 v[56:59], v[68:71], v[206:209], v[56:59]
	v_mfma_f32_16x16x32_f16 v[28:31], v[52:55], v[214:217], v[28:31]
	v_mfma_f32_16x16x32_f16 v[24:27], v[68:71], v[214:217], v[24:27]
	v_mfma_f32_16x16x32_f16 v[12:15], v[52:55], v[222:225], v[12:15]
	v_mfma_f32_16x16x32_f16 v[8:11], v[68:71], v[222:225], v[8:11]
	v_mfma_f32_16x16x32_f16 v[32:35], v[156:159], v[194:197], v[32:35]
	v_mfma_f32_16x16x32_f16 v[68:71], v[168:171], v[198:201], v[32:35]
	v_mfma_f32_16x16x32_f16 v[32:35], v[186:189], v[194:197], v[36:39]
	v_mfma_f32_16x16x32_f16 v[64:67], v[190:193], v[198:201], v[32:35]
	v_mfma_f32_16x16x32_f16 v[32:35], v[156:159], v[202:205], v[40:43]
	v_mfma_f32_16x16x32_f16 v[52:55], v[168:171], v[206:209], v[32:35]
	v_mfma_f32_16x16x32_f16 v[32:35], v[186:189], v[202:205], v[44:47]
	v_mfma_f32_16x16x32_f16 v[20:23], v[156:159], v[210:213], v[20:23]
	v_mfma_f32_16x16x32_f16 v[16:19], v[186:189], v[210:213], v[16:19]
	v_mfma_f32_16x16x32_f16 v[4:7], v[156:159], v[218:221], v[4:7]
	v_mfma_f32_16x16x32_f16 v[0:3], v[186:189], v[218:221], v[0:3]
	v_mfma_f32_16x16x32_f16 v[48:51], v[190:193], v[206:209], v[32:35]
	v_mfma_f32_16x16x32_f16 v[20:23], v[168:171], v[214:217], v[20:23]
	v_mfma_f32_16x16x32_f16 v[16:19], v[190:193], v[214:217], v[16:19]
	v_mfma_f32_16x16x32_f16 v[4:7], v[168:171], v[222:225], v[4:7]
	v_mfma_f32_16x16x32_f16 v[0:3], v[190:193], v[222:225], v[0:3]
	s_setprio 0
	s_barrier
	s_add_i32 s61, s61, 2
	s_add_u32 s54, s54, 0x100
	s_addc_u32 s55, s55, 0
	s_add_u32 s49, s49, 0x100
	s_addc_u32 s60, s60, 0
	s_cmp_gt_u32 s61, 13
	s_branch .LBB0_904

; #define PG8_STAGE(bufoff, gbase, voff) do { _Pragma("unroll") for (int _i = 0; _i < 2; ++_i) \
;         __builtin_amdgcn_global_load_lds((const unsigned*)((const char*)(gbase) + (voff)[_i]), (PG8_LAS unsigned*)(lds + (bufoff) + ldsw + _i * 8192), 16, 0, 0); } while (0)
; #define PG8_LDA(dst, b, h) do { _Pragma("unroll") for (int m = 0; m < 4; ++m) _Pragma("unroll") for (int k = 0; k < 2; ++k) dst[m][k] = *(const PG8_LAS bf16x8*)(lds + PG8_SA(b, h) + aoff + m * 2048 + k * 1024); } while (0)
; #define PG8_LDB(dst, b, h) do { _Pragma("unroll") for (int n = 0; n < 2; ++n) _Pragma("unroll") for (int k = 0; k < 2; ++k) dst[n][k] = *(const PG8_LAS bf16x8*)(lds + PG8_SB(b, h) + boff + n * 2048 + k * 1024); } while (0)
; #define PG8_MMA(ai, bj, At, Bt) do { __builtin_amdgcn_s_setprio(1); _Pragma("unroll") for (int m = 0; m < 4; ++m) _Pragma("unroll") for (int n = 0; n < 2; ++n) _Pragma("unroll") for (int k = 0; k < 2; ++k) \
;         acc[ai][bj][m][n] = mma16<F16>(Bt[n][k], At[m][k], acc[ai][bj][m][n]); __builtin_amdgcn_s_setprio(0); } while (0)
; #define PG8_WAIT_V(n) asm volatile("s_waitcnt vmcnt(" #n ")" ::: "memory")
; #define PG8_WAIT_L(n) asm volatile("s_waitcnt lgkmcnt(" #n ")" ::: "memory")
; #define PG8_BAR __builtin_amdgcn_s_barrier()
; #define PG8_SCHED __builtin_amdgcn_sched_barrier(0)
; template <class Epi, class Sched, bool ALIGN_EPI = false, bool SP2 = false, bool F16 = false>
; __device__ __forceinline__ void gemm_phase(PG8_LAS unsigned char* lds, const Gemm g, const Sched& S, const Epi& E) {
;     ...
;         const bool has_next = S.next(ui + 1, nxt);
;         const char* nA = has_next ? (const char*)g.A + (size_t)nxt.pm * tstep : cA; const char* nB = has_next ? (const char*)g.Bt + (size_t)nxt.pn * tstep + (nxt.pm >= g.mhalf ? g.bstride : (size_t)0) : cB;
;     ...
;             PG8_LDB(B0, 0, 0); PG8_LDB(B1, 0, 1); PG8_SCHED; PG8_LDA(At, 0, 0); PG8_STAGE(PG8_SA(1, 1), a1 + hstep, voffA);
;             PG8_WAIT_V(8); PG8_WAIT_L(0); PG8_BAR; PG8_MMA(0, 0, At, B0); PG8_MMA(0, 1, At, B1); PG8_BAR; PG8_SCHED;
;             PG8_LDA(At, 0, 1); PG8_STAGE(PG8_SB(0, 0), b2, voffB); PG8_STAGE(PG8_SB(0, 1), b2 + hstep, voffB); PG8_STAGE(PG8_SA(0, 0), a2, voffA);
;             PG8_WAIT_V(8); PG8_WAIT_L(0); PG8_BAR; PG8_MMA(1, 0, At, B0); PG8_MMA(1, 1, At, B1); PG8_BAR; PG8_SCHED;
.LBB0_903:
	s_ashr_i32 s49, s48, 31
	s_lshl_b64 s[4:5], s[48:49], 19
	s_add_u32 s50, s96, s4
	s_addc_u32 s51, s97, s5
	s_and_b64 s[4:5], s[40:41], exec
	s_cselect_b32 s4, s51, s55
	s_cselect_b32 s5, s50, s54
	s_ashr_i32 s47, s46, 31
	s_lshl_b64 s[52:53], s[46:47], 19
	s_add_u32 s37, s6, s52
	s_addc_u32 s47, s7, s53
	s_cmp_gt_i32 s48, 63
	s_cselect_b32 s49, 0xb00000, 0
	s_add_u32 s52, s37, s49
	s_addc_u32 s53, s47, 0
	s_and_b64 s[58:59], s[40:41], exec
	s_cselect_b32 s37, s53, s57
	s_cselect_b32 s47, s52, s56
	s_add_u32 s54, s54, 0x40080
	s_addc_u32 s55, s55, 0
	s_add_u32 s49, s56, 0x100
	s_addc_u32 s60, s57, 0
	s_mov_b32 s61, -2
	v_add_u32_e32 v172, 0x10000, v163
	s_cmp_eq_u32 s29, 1
	s_cbranch_scc1 .Lgu_first
	s_add_u32 s56, s54, 0xfffc0080
	s_addc_u32 s57, s55, -1
	s_add_i32 s62, 0, 0x10000
	s_cmp_eq_u32 s61, 12
	s_cselect_b32 s59, s4, s57
	s_cselect_b32 s58, s5, s56
	s_cselect_b32 s57, s37, s60
	s_cselect_b32 s56, s47, s49
	s_add_i32 s64, 0, 0x14000
	ds_read_b128 v[32:35], v172
	ds_read_b128 v[36:39], v172 offset:1024
	ds_read_b128 v[40:43], v172 offset:2048
	ds_read_b128 v[44:47], v172 offset:3072
	ds_read_b128 v[156:159], v172 offset:16384
	ds_read_b128 v[168:171], v172 offset:17408
	ds_read_b128 v[186:189], v172 offset:18432
	ds_read_b128 v[190:193], v172 offset:19456
	s_add_i32 m0, s9, 0xc000
	ds_read_b128 v[194:197], v165
	ds_read_b128 v[198:201], v165 offset:1024
	ds_read_b128 v[202:205], v165 offset:2048
	ds_read_b128 v[206:209], v165 offset:3072
	ds_read_b128 v[210:213], v165 offset:4096
	ds_read_b128 v[214:217], v165 offset:5120
	ds_read_b128 v[218:221], v165 offset:6144
	ds_read_b128 v[222:225], v165 offset:7168
	s_add_i32 m0, s9, 0xe000
	s_nop 0
	s_waitcnt vmcnt(16)
	s_waitcnt lgkmcnt(0)
	s_barrier
	s_setprio 1
	s_waitcnt lgkmcnt(0)
	v_mfma_f32_16x16x32_f16 v[142:145], v[32:35], v[194:197], 0
	v_mfma_f32_16x16x32_f16 v[138:141], v[40:43], v[194:197], 0
	v_mfma_f32_16x16x32_f16 v[124:127], v[32:35], v[202:205], 0
	v_mfma_f32_16x16x32_f16 v[120:123], v[40:43], v[202:205], 0
	v_mfma_f32_16x16x32_f16 v[108:111], v[32:35], v[210:213], 0
	v_mfma_f32_16x16x32_f16 v[104:107], v[40:43], v[210:213], 0
	v_mfma_f32_16x16x32_f16 v[92:95], v[32:35], v[218:221], 0
	v_mfma_f32_16x16x32_f16 v[88:91], v[40:43], v[218:221], 0
	v_mfma_f32_16x16x32_f16 v[142:145], v[36:39], v[198:201], v[142:145]
	v_mfma_f32_16x16x32_f16 v[138:141], v[44:47], v[198:201], v[138:141]
	v_mfma_f32_16x16x32_f16 v[124:127], v[36:39], v[206:209], v[124:127]
	v_mfma_f32_16x16x32_f16 v[120:123], v[44:47], v[206:209], v[120:123]
	v_mfma_f32_16x16x32_f16 v[108:111], v[36:39], v[214:217], v[108:111]
	v_mfma_f32_16x16x32_f16 v[104:107], v[44:47], v[214:217], v[104:107]
	v_mfma_f32_16x16x32_f16 v[92:95], v[36:39], v[222:225], v[92:95]
	v_mfma_f32_16x16x32_f16 v[88:91], v[44:47], v[222:225], v[88:91]
	v_mfma_f32_16x16x32_f16 v[134:137], v[156:159], v[194:197], 0
	v_mfma_f32_16x16x32_f16 v[130:133], v[186:189], v[194:197], 0
	v_mfma_f32_16x16x32_f16 v[116:119], v[156:159], v[202:205], 0
	v_mfma_f32_16x16x32_f16 v[112:115], v[186:189], v[202:205], 0
	v_mfma_f32_16x16x32_f16 v[100:103], v[156:159], v[210:213], 0
	v_mfma_f32_16x16x32_f16 v[96:99], v[186:189], v[210:213], 0
	v_mfma_f32_16x16x32_f16 v[84:87], v[156:159], v[218:221], 0
	v_mfma_f32_16x16x32_f16 v[80:83], v[186:189], v[218:221], 0
	v_mfma_f32_16x16x32_f16 v[134:137], v[168:171], v[198:201], v[134:137]
	v_mfma_f32_16x16x32_f16 v[130:133], v[190:193], v[198:201], v[130:133]
	v_mfma_f32_16x16x32_f16 v[116:119], v[168:171], v[206:209], v[116:119]
	v_mfma_f32_16x16x32_f16 v[112:115], v[190:193], v[206:209], v[112:115]
	v_mfma_f32_16x16x32_f16 v[100:103], v[168:171], v[214:217], v[100:103]
	v_mfma_f32_16x16x32_f16 v[96:99], v[190:193], v[214:217], v[96:99]
	v_mfma_f32_16x16x32_f16 v[84:87], v[168:171], v[222:225], v[84:87]
	v_mfma_f32_16x16x32_f16 v[80:83], v[190:193], v[222:225], v[80:83]
	s_setprio 0
	s_barrier
	s_add_u32 s98, s56, s16
	s_addc_u32 s99, s57, s17
	s_add_u32 s100, s58, s16
	s_addc_u32 s101, s59, s17
	s_add_i32 s62, s62, s8
	s_mov_b32 m0, s62
	ds_read_b128 v[194:197], v165 offset:16384
	ds_read_b128 v[198:201], v165 offset:17408
	ds_read_b128 v[202:205], v165 offset:18432
	ds_read_b128 v[206:209], v165 offset:19456
	ds_read_b128 v[210:213], v165 offset:20480
	ds_read_b128 v[214:217], v165 offset:21504
	ds_read_b128 v[218:221], v165 offset:22528
	ds_read_b128 v[222:225], v165 offset:23552
	global_load_lds_dwordx4 v128, s[56:57]
	s_add_i32 m0, s62, 0x2000
	s_add_u32 s62, s56, 0x40000
	s_addc_u32 s63, s57, 0
	s_add_i32 s64, s64, s8
	global_load_lds_dwordx4 v146, s[56:57]
	s_mov_b32 m0, s64
	s_nop 0
	global_load_lds_dwordx4 v128, s[62:63]
	s_add_i32 m0, s64, 0x2000
	s_nop 0
	global_load_lds_dwordx4 v146, s[62:63]
	s_mov_b32 m0, s9
	s_nop 0
	global_load_lds_dwordx4 v150, s[58:59]
	s_mov_b32 m0, s10
	s_nop 0
	global_load_lds_dwordx4 v148, s[58:59]
	s_waitcnt vmcnt(16)
	s_waitcnt lgkmcnt(0)
	s_barrier
; #define PG8_STAGE(bufoff, gbase, voff) do { _Pragma("unroll") for (int _i = 0; _i < 2; ++_i) \
;         __builtin_amdgcn_global_load_lds((const unsigned*)((const char*)(gbase) + (voff)[_i]), (PG8_LAS unsigned*)(lds + (bufoff) + ldsw + _i * 8192), 16, 0, 0); } while (0)
; #define PG8_LDA(dst, b, h) do { _Pragma("unroll") for (int m = 0; m < 4; ++m) _Pragma("unroll") for (int k = 0; k < 2; ++k) dst[m][k] = *(const PG8_LAS bf16x8*)(lds + PG8_SA(b, h) + aoff + m * 2048 + k * 1024); } while (0)
; #define PG8_LDB(dst, b, h) do { _Pragma("unroll") for (int n = 0; n < 2; ++n) _Pragma("unroll") for (int k = 0; k < 2; ++k) dst[n][k] = *(const PG8_LAS bf16x8*)(lds + PG8_SB(b, h) + boff + n * 2048 + k * 1024); } while (0)
; #define PG8_MMA(ai, bj, At, Bt) do { __builtin_amdgcn_s_setprio(1); _Pragma("unroll") for (int m = 0; m < 4; ++m) _Pragma("unroll") for (int n = 0; n < 2; ++n) _Pragma("unroll") for (int k = 0; k < 2; ++k) \
;         acc[ai][bj][m][n] = mma16<F16>(Bt[n][k], At[m][k], acc[ai][bj][m][n]); __builtin_amdgcn_s_setprio(0); } while (0)
; #define PG8_WAIT_V(n) asm volatile("s_waitcnt vmcnt(" #n ")" ::: "memory")
; #define PG8_WAIT_L(n) asm volatile("s_waitcnt lgkmcnt(" #n ")" ::: "memory")
; #define PG8_BAR __builtin_amdgcn_s_barrier()
; #define PG8_SCHED __builtin_amdgcn_sched_barrier(0)
; template <class Epi, class Sched, bool ALIGN_EPI = false, bool SP2 = false, bool F16 = false>
; __device__ __forceinline__ void gemm_phase(PG8_LAS unsigned char* lds, const Gemm g, const Sched& S, const Epi& E) {
;     ...
;             PG8_WAIT_V(8); PG8_WAIT_L(0); PG8_BAR; PG8_MMA(1, 0, At, B0); PG8_MMA(1, 1, At, B1); PG8_BAR; PG8_SCHED;
;             PG8_LDB(B0, 1, 0); PG8_LDB(B1, 1, 1); PG8_SCHED; PG8_LDA(At, 1, 0); PG8_STAGE(PG8_SA(0, 1), a2 + hstep, voffA);
;             PG8_WAIT_V(8); PG8_WAIT_L(0); PG8_BAR; PG8_MMA(0, 0, At, B0); PG8_MMA(0, 1, At, B1); PG8_BAR; PG8_SCHED;
;             PG8_LDA(At, 1, 1); PG8_STAGE(PG8_SB(1, 0), b3, voffB); PG8_STAGE(PG8_SB(1, 1), b3 + hstep, voffB); PG8_STAGE(PG8_SA(1, 0), a3, voffA);
	s_setprio 1
	s_waitcnt lgkmcnt(0)
	v_mfma_f32_16x16x32_f16 v[76:79], v[32:35], v[194:197], 0
	v_mfma_f32_16x16x32_f16 v[72:75], v[40:43], v[194:197], 0
	v_mfma_f32_16x16x32_f16 v[60:63], v[32:35], v[202:205], 0
	v_mfma_f32_16x16x32_f16 v[56:59], v[40:43], v[202:205], 0
	v_mfma_f32_16x16x32_f16 v[28:31], v[32:35], v[210:213], 0
	v_mfma_f32_16x16x32_f16 v[24:27], v[40:43], v[210:213], 0
	v_mfma_f32_16x16x32_f16 v[12:15], v[32:35], v[218:221], 0
	v_mfma_f32_16x16x32_f16 v[8:11], v[40:43], v[218:221], 0
	v_mfma_f32_16x16x32_f16 v[76:79], v[36:39], v[198:201], v[76:79]
	v_mfma_f32_16x16x32_f16 v[72:75], v[44:47], v[198:201], v[72:75]
	v_mfma_f32_16x16x32_f16 v[60:63], v[36:39], v[206:209], v[60:63]
	v_mfma_f32_16x16x32_f16 v[56:59], v[44:47], v[206:209], v[56:59]
	v_mfma_f32_16x16x32_f16 v[28:31], v[36:39], v[214:217], v[28:31]
	v_mfma_f32_16x16x32_f16 v[24:27], v[44:47], v[214:217], v[24:27]
	v_mfma_f32_16x16x32_f16 v[12:15], v[36:39], v[222:225], v[12:15]
	v_mfma_f32_16x16x32_f16 v[8:11], v[44:47], v[222:225], v[8:11]
	v_mfma_f32_16x16x32_f16 v[20:23], v[156:159], v[210:213], 0
	v_mfma_f32_16x16x32_f16 v[16:19], v[186:189], v[210:213], 0
	v_mfma_f32_16x16x32_f16 v[4:7], v[156:159], v[218:221], 0
	v_mfma_f32_16x16x32_f16 v[0:3], v[186:189], v[218:221], 0
	v_mfma_f32_16x16x32_f16 v[32:35], v[156:159], v[194:197], 0
	v_mfma_f32_16x16x32_f16 v[36:39], v[186:189], v[194:197], 0
	v_mfma_f32_16x16x32_f16 v[40:43], v[156:159], v[202:205], 0
	v_mfma_f32_16x16x32_f16 v[44:47], v[186:189], v[202:205], 0
	v_mfma_f32_16x16x32_f16 v[20:23], v[168:171], v[214:217], v[20:23]
	v_mfma_f32_16x16x32_f16 v[16:19], v[190:193], v[214:217], v[16:19]
	v_mfma_f32_16x16x32_f16 v[4:7], v[168:171], v[222:225], v[4:7]
	v_mfma_f32_16x16x32_f16 v[0:3], v[190:193], v[222:225], v[0:3]
	v_mfma_f32_16x16x32_f16 v[32:35], v[168:171], v[198:201], v[32:35]
	v_mfma_f32_16x16x32_f16 v[36:39], v[190:193], v[198:201], v[36:39]
	v_mfma_f32_16x16x32_f16 v[40:43], v[168:171], v[206:209], v[40:43]
	v_mfma_f32_16x16x32_f16 v[44:47], v[190:193], v[206:209], v[44:47]
	s_setprio 0
	s_barrier
	s_add_i32 s62, 0, 0x18000
	s_add_i32 s63, 0, 0x1c000
	ds_read_b128 v[48:51], v172 offset:32768
	ds_read_b128 v[52:55], v172 offset:33792
	ds_read_b128 v[64:67], v172 offset:34816
	ds_read_b128 v[68:71], v172 offset:35840
	ds_read_b128 v[156:159], v172 offset:49152
	ds_read_b128 v[168:171], v172 offset:50176
	ds_read_b128 v[186:189], v172 offset:51200
	ds_read_b128 v[190:193], v172 offset:52224
	s_add_u32 s58, s58, 0x40000
	s_addc_u32 s59, s59, 0
	s_mov_b32 m0, s11
	ds_read_b128 v[194:197], v165 offset:32768
	ds_read_b128 v[198:201], v165 offset:33792
	ds_read_b128 v[202:205], v165 offset:34816
	ds_read_b128 v[206:209], v165 offset:35840
	ds_read_b128 v[210:213], v165 offset:36864
	ds_read_b128 v[214:217], v165 offset:37888
	ds_read_b128 v[218:221], v165 offset:38912
	ds_read_b128 v[222:225], v165 offset:39936
	global_load_lds_dwordx4 v150, s[58:59]
	s_mov_b32 m0, s13
	s_nop 0
	global_load_lds_dwordx4 v148, s[58:59]
	s_waitcnt vmcnt(16)
	s_waitcnt lgkmcnt(0)
	s_barrier
	s_setprio 1
	s_waitcnt lgkmcnt(0)
	v_mfma_f32_16x16x32_f16 v[142:145], v[48:51], v[194:197], v[142:145]
	v_mfma_f32_16x16x32_f16 v[138:141], v[64:67], v[194:197], v[138:141]
	v_mfma_f32_16x16x32_f16 v[124:127], v[48:51], v[202:205], v[124:127]
	v_mfma_f32_16x16x32_f16 v[120:123], v[64:67], v[202:205], v[120:123]
	v_mfma_f32_16x16x32_f16 v[108:111], v[48:51], v[210:213], v[108:111]
	v_mfma_f32_16x16x32_f16 v[104:107], v[64:67], v[210:213], v[104:107]
	v_mfma_f32_16x16x32_f16 v[92:95], v[48:51], v[218:221], v[92:95]
	v_mfma_f32_16x16x32_f16 v[88:91], v[64:67], v[218:221], v[88:91]
	v_mfma_f32_16x16x32_f16 v[142:145], v[52:55], v[198:201], v[142:145]
	v_mfma_f32_16x16x32_f16 v[138:141], v[68:71], v[198:201], v[138:141]
	v_mfma_f32_16x16x32_f16 v[124:127], v[52:55], v[206:209], v[124:127]
	v_mfma_f32_16x16x32_f16 v[120:123], v[68:71], v[206:209], v[120:123]
	v_mfma_f32_16x16x32_f16 v[108:111], v[52:55], v[214:217], v[108:111]
	v_mfma_f32_16x16x32_f16 v[104:107], v[68:71], v[214:217], v[104:107]
	v_mfma_f32_16x16x32_f16 v[92:95], v[52:55], v[222:225], v[92:95]
	v_mfma_f32_16x16x32_f16 v[88:91], v[68:71], v[222:225], v[88:91]
	v_mfma_f32_16x16x32_f16 v[134:137], v[156:159], v[194:197], v[134:137]
	v_mfma_f32_16x16x32_f16 v[130:133], v[186:189], v[194:197], v[130:133]
	v_mfma_f32_16x16x32_f16 v[116:119], v[156:159], v[202:205], v[116:119]
	v_mfma_f32_16x16x32_f16 v[112:115], v[186:189], v[202:205], v[112:115]
	v_mfma_f32_16x16x32_f16 v[100:103], v[156:159], v[210:213], v[100:103]
	v_mfma_f32_16x16x32_f16 v[96:99], v[186:189], v[210:213], v[96:99]
	v_mfma_f32_16x16x32_f16 v[84:87], v[156:159], v[218:221], v[84:87]
	v_mfma_f32_16x16x32_f16 v[80:83], v[186:189], v[218:221], v[80:83]
	v_mfma_f32_16x16x32_f16 v[134:137], v[168:171], v[198:201], v[134:137]
	v_mfma_f32_16x16x32_f16 v[130:133], v[190:193], v[198:201], v[130:133]
	v_mfma_f32_16x16x32_f16 v[116:119], v[168:171], v[206:209], v[116:119]
	v_mfma_f32_16x16x32_f16 v[112:115], v[190:193], v[206:209], v[112:115]
	v_mfma_f32_16x16x32_f16 v[100:103], v[168:171], v[214:217], v[100:103]
	v_mfma_f32_16x16x32_f16 v[96:99], v[190:193], v[214:217], v[96:99]
	v_mfma_f32_16x16x32_f16 v[84:87], v[168:171], v[222:225], v[84:87]
	v_mfma_f32_16x16x32_f16 v[80:83], v[190:193], v[222:225], v[80:83]
	s_setprio 0
	s_barrier
; #define PG8_STAGE(bufoff, gbase, voff) do { _Pragma("unroll") for (int _i = 0; _i < 2; ++_i) \
;         __builtin_amdgcn_global_load_lds((const unsigned*)((const char*)(gbase) + (voff)[_i]), (PG8_LAS unsigned*)(lds + (bufoff) + ldsw + _i * 8192), 16, 0, 0); } while (0)
; #define PG8_LDA(dst, b, h) do { _Pragma("unroll") for (int m = 0; m < 4; ++m) _Pragma("unroll") for (int k = 0; k < 2; ++k) dst[m][k] = *(const PG8_LAS bf16x8*)(lds + PG8_SA(b, h) + aoff + m * 2048 + k * 1024); } while (0)
; #define PG8_MMA(ai, bj, At, Bt) do { __builtin_amdgcn_s_setprio(1); _Pragma("unroll") for (int m = 0; m < 4; ++m) _Pragma("unroll") for (int n = 0; n < 2; ++n) _Pragma("unroll") for (int k = 0; k < 2; ++k) \
;         acc[ai][bj][m][n] = mma16<F16>(Bt[n][k], At[m][k], acc[ai][bj][m][n]); __builtin_amdgcn_s_setprio(0); } while (0)
; #define PG8_WAIT_V(n) asm volatile("s_waitcnt vmcnt(" #n ")" ::: "memory")
; #define PG8_WAIT_L(n) asm volatile("s_waitcnt lgkmcnt(" #n ")" ::: "memory")
; #define PG8_BAR __builtin_amdgcn_s_barrier()
; #define PG8_SCHED __builtin_amdgcn_sched_barrier(0)
; template <class Epi, class Sched, bool ALIGN_EPI = false, bool SP2 = false, bool F16 = false>
; __device__ __forceinline__ void gemm_phase(PG8_LAS unsigned char* lds, const Gemm g, const Sched& S, const Epi& E) {
;     ...
;             PG8_LDA(At, 1, 1); PG8_STAGE(PG8_SB(1, 0), b3, voffB); PG8_STAGE(PG8_SB(1, 1), b3 + hstep, voffB); PG8_STAGE(PG8_SA(1, 0), a3, voffA);
;             PG8_WAIT_V(8); PG8_WAIT_L(0); PG8_BAR; PG8_MMA(1, 0, At, B0); PG8_MMA(1, 1, At, B1); PG8_BAR; PG8_SCHED;
	s_add_i32 s58, s62, s8
	s_mov_b32 m0, s58
	ds_read_b128 v[194:197], v165 offset:49152
	ds_read_b128 v[198:201], v165 offset:50176
	ds_read_b128 v[202:205], v165 offset:51200
	ds_read_b128 v[206:209], v165 offset:52224
	ds_read_b128 v[210:213], v165 offset:53248
	ds_read_b128 v[214:217], v165 offset:54272
	ds_read_b128 v[218:221], v165 offset:55296
	ds_read_b128 v[222:225], v165 offset:56320
	global_load_lds_dwordx4 v128, s[98:99]
	s_add_i32 m0, s58, 0x2000
	s_add_u32 s56, s56, 0x40080
	s_addc_u32 s57, s57, 0
	s_add_i32 s58, s63, s8
	global_load_lds_dwordx4 v146, s[98:99]
	s_mov_b32 m0, s58
	s_nop 0
	global_load_lds_dwordx4 v128, s[56:57]
	s_add_i32 m0, s58, 0x2000
	s_nop 0
	global_load_lds_dwordx4 v146, s[56:57]
	s_mov_b32 m0, s20
	s_nop 0
	global_load_lds_dwordx4 v150, s[100:101]
	s_mov_b32 m0, s21
	s_nop 0
	global_load_lds_dwordx4 v148, s[100:101]
	s_waitcnt vmcnt(8)
	s_waitcnt lgkmcnt(0)
	s_barrier
	s_setprio 1
	s_waitcnt lgkmcnt(0)
	v_mfma_f32_16x16x32_f16 v[76:79], v[48:51], v[194:197], v[76:79]
	v_mfma_f32_16x16x32_f16 v[72:75], v[64:67], v[194:197], v[72:75]
	v_mfma_f32_16x16x32_f16 v[60:63], v[48:51], v[202:205], v[60:63]
	v_mfma_f32_16x16x32_f16 v[56:59], v[64:67], v[202:205], v[56:59]
	v_mfma_f32_16x16x32_f16 v[28:31], v[48:51], v[210:213], v[28:31]
	v_mfma_f32_16x16x32_f16 v[24:27], v[64:67], v[210:213], v[24:27]
	v_mfma_f32_16x16x32_f16 v[12:15], v[48:51], v[218:221], v[12:15]
	v_mfma_f32_16x16x32_f16 v[8:11], v[64:67], v[218:221], v[8:11]
	v_mfma_f32_16x16x32_f16 v[76:79], v[52:55], v[198:201], v[76:79]
	v_mfma_f32_16x16x32_f16 v[72:75], v[68:71], v[198:201], v[72:75]
	v_mfma_f32_16x16x32_f16 v[60:63], v[52:55], v[206:209], v[60:63]
	v_mfma_f32_16x16x32_f16 v[56:59], v[68:71], v[206:209], v[56:59]
	v_mfma_f32_16x16x32_f16 v[28:31], v[52:55], v[214:217], v[28:31]
	v_mfma_f32_16x16x32_f16 v[24:27], v[68:71], v[214:217], v[24:27]
	v_mfma_f32_16x16x32_f16 v[12:15], v[52:55], v[222:225], v[12:15]
	v_mfma_f32_16x16x32_f16 v[8:11], v[68:71], v[222:225], v[8:11]
	v_mfma_f32_16x16x32_f16 v[32:35], v[156:159], v[194:197], v[32:35]
	v_mfma_f32_16x16x32_f16 v[68:71], v[168:171], v[198:201], v[32:35]
	v_mfma_f32_16x16x32_f16 v[32:35], v[186:189], v[194:197], v[36:39]
	v_mfma_f32_16x16x32_f16 v[64:67], v[190:193], v[198:201], v[32:35]
	v_mfma_f32_16x16x32_f16 v[32:35], v[156:159], v[202:205], v[40:43]
	v_mfma_f32_16x16x32_f16 v[52:55], v[168:171], v[206:209], v[32:35]
	v_mfma_f32_16x16x32_f16 v[32:35], v[186:189], v[202:205], v[44:47]
	v_mfma_f32_16x16x32_f16 v[20:23], v[156:159], v[210:213], v[20:23]
	v_mfma_f32_16x16x32_f16 v[16:19], v[186:189], v[210:213], v[16:19]
	v_mfma_f32_16x16x32_f16 v[4:7], v[156:159], v[218:221], v[4:7]
	v_mfma_f32_16x16x32_f16 v[0:3], v[186:189], v[218:221], v[0:3]
	v_mfma_f32_16x16x32_f16 v[48:51], v[190:193], v[206:209], v[32:35]
	v_mfma_f32_16x16x32_f16 v[20:23], v[168:171], v[214:217], v[20:23]
	v_mfma_f32_16x16x32_f16 v[16:19], v[190:193], v[214:217], v[16:19]
	v_mfma_f32_16x16x32_f16 v[4:7], v[168:171], v[222:225], v[4:7]
	v_mfma_f32_16x16x32_f16 v[0:3], v[190:193], v[222:225], v[0:3]
	s_setprio 0
	s_barrier
	s_add_i32 s61, s61, 2
	s_add_u32 s54, s54, 0x100
	s_addc_u32 s55, s55, 0
	s_add_u32 s49, s49, 0x100
	s_addc_u32 s60, s60, 0
	s_cmp_gt_u32 s61, 13

; __device__ __forceinline__ unsigned pk_bf16(float lo, float hi) { f32x2 v = {lo, hi}; bf16x2_t b = __builtin_convertvector(v, bf16x2_t); return __builtin_bit_cast(unsigned, b); }
;     __device__ __forceinline__ void operator()(const f32x4 (&acc)[2][2][4][2], const Unit& u, int wr, int wc, int fr, int fq) const {
;         const int row0 = u.pm * BM + wr * 64 + fr; const int col0 = u.pn * HALF + wc * 32 + 8 * fq;
;         const float* bp = bias + (size_t)((u.pm * BM) >> 14) * 5632 + u.pn * BM + wc * 32 + 8 * fq;
;         f32x4 bz[2][2];
; #pragma unroll
;         for (int bj = 0; bj < 2; ++bj)
; #pragma unroll
;             for (int n = 0; n < 2; ++n) bz[bj][n] = *(const f32x4*)(bp + bj * HALF + 4 * n);
; #pragma unroll
;         for (int ai = 0; ai < 2; ++ai)
; #pragma unroll
;             for (int m = 0; m < 4; ++m) {
;                 float o[8]; const float rv = rsqrtf(rowss[row0 + ai * HALF + m * 16] * (1.0f / 1024.0f) + 1e-6f);
; #pragma unroll
;                 for (int n = 0; n < 2; ++n)
; #pragma unroll
;                     for (int j = 0; j < 4; ++j) { const float g = acc[ai][0][m][n][j] * rv + bz[0][n][j], up = acc[ai][1][m][n][j] * rv + bz[1][n][j];
;                         o[4 * n + j] = g * __builtin_amdgcn_rcpf(1.0f + __expf(-g)) * up; }
;                 u32x4 w; w.x = pk_bf16(o[0], o[1]); w.y = pk_bf16(o[2], o[3]); w.z = pk_bf16(o[4], o[5]); w.w = pk_bf16(o[6], o[7]);
;                 *(u32x4*)(act + (size_t)(row0 + ai * HALF + m * 16) * 2816 + col0) = w;
.LBB0_907:
	s_ashr_i32 s4, s34, 6
	s_mul_hi_i32 s5, s4, 0x5800
	s_mulk_i32 s4, 0x5800
	v_lshl_add_u32 v156, s34, 8, v162
	s_add_u32 s34, s14, s4
	s_addc_u32 s37, s15, s5
	s_lshl_b32 s4, s31, 8
	s_ashr_i32 s5, s4, 31
	s_lshl_b64 s[4:5], s[4:5], 2
	s_add_u32 s4, s34, s4
	s_addc_u32 s5, s37, s5
	s_add_u32 s4, s4, s30
	v_ashrrev_i32_e32 v157, 31, v156
	s_addc_u32 s5, s5, 0
	v_lshl_add_u64 v[158:159], v[156:157], 2, s[42:43]
	v_mov_b32_e32 v36, v242
	v_mov_b32_e32 v37, v243
	v_mov_b32_e32 v38, v244
	v_mov_b32_e32 v39, v245
	v_mov_b32_e32 v44, v246
	v_mov_b32_e32 v45, v247
	v_mov_b32_e32 v46, v248
	v_mov_b32_e32 v47, v249
	v_mov_b32_e32 v32, v174
	v_mov_b32_e32 v33, v175
	v_mov_b32_e32 v34, v176
	v_mov_b32_e32 v35, v177
	v_mov_b32_e32 v40, v238
	v_mov_b32_e32 v41, v239
	v_mov_b32_e32 v42, v240
	v_mov_b32_e32 v43, v241
	v_mov_b32_e32 v157, v147
	v_mov_b32_e32 v186, v149
	v_mov_b32_e32 v187, v151
	v_mov_b32_e32 v188, v153
	v_mov_b32_e32 v189, v155
	v_mov_b32_e32 v190, v167
	v_mov_b32_e32 v191, v173
	v_mov_b32_e32 v192, v250
	v_lshl_or_b32 v160, s31, 7, v164
	v_ashrrev_i32_e32 v161, 31, v160
	s_movk_i32 s12, 0x1600
	s_mov_b64 s[54:55], -1
	s_waitcnt vmcnt(8)
	s_add_u32 s98, s50, 0x40080
	s_addc_u32 s99, s51, 0
	s_add_i32 m0, s9, 0xc000
	s_nop 0
	global_load_lds_dwordx4 v152, s[98:99]
	s_add_i32 m0, s9, 0xe000
	s_nop 0
	global_load_lds_dwordx4 v154, s[98:99]
	v_fmamk_f32 v157, v157, 0x3a800000, v227
	s_nop 0
	v_rsq_f32_e32 v157, v157
	s_nop 0
	v_mov_b32_e32 v168, v157
	v_pk_fma_f32 v[142:143], v[142:143], v[168:169], v[44:45] op_sel_hi:[1,0,1]
	v_pk_fma_f32 v[134:135], v[134:135], v[168:169], v[40:41] op_sel_hi:[1,0,1]
	v_mul_f32_e32 v157, 0xbfb8aa3b, v142
	v_exp_f32_e32 v157, v157
	v_pk_fma_f32 v[136:137], v[136:137], v[168:169], v[42:43] op_sel_hi:[1,0,1]
	v_pk_fma_f32 v[138:139], v[138:139], v[168:169], v[36:37] op_sel_hi:[1,0,1]
	v_pk_fma_f32 v[130:131], v[130:131], v[168:169], v[32:33] op_sel_hi:[1,0,1]
	v_add_f32_e32 v157, 1.0, v157
	v_rcp_f32_e32 v170, v157
	v_mul_f32_e32 v157, 0xbfb8aa3b, v143
	v_exp_f32_e32 v157, v157
	v_pk_fma_f32 v[132:133], v[132:133], v[168:169], v[34:35] op_sel_hi:[1,0,1]
	v_add_f32_e32 v157, 1.0, v157
	v_rcp_f32_e32 v171, v157
	s_nop 0
	v_pk_mul_f32 v[142:143], v[142:143], v[170:171]
	s_nop 0
	v_pk_mul_f32 v[134:135], v[134:135], v[142:143]
	v_pk_fma_f32 v[142:143], v[144:145], v[168:169], v[46:47] op_sel_hi:[1,0,1]
	s_nop 0
	v_mul_f32_e32 v144, 0xbfb8aa3b, v142
	v_mul_f32_e32 v145, 0xbfb8aa3b, v143
	v_exp_f32_e32 v144, v144
	v_exp_f32_e32 v145, v145
	v_add_f32_e32 v144, 1.0, v144
	v_add_f32_e32 v145, 1.0, v145
	v_rcp_f32_e32 v144, v144
	v_rcp_f32_e32 v145, v145
	s_nop 0
	v_pk_mul_f32 v[142:143], v[142:143], v[144:145]
	s_nop 0
	v_pk_mul_f32 v[136:137], v[136:137], v[142:143]
	v_mul_f32_e32 v142, 0xbfb8aa3b, v138
	v_mul_f32_e32 v143, 0xbfb8aa3b, v139
	v_exp_f32_e32 v142, v142
	v_exp_f32_e32 v143, v143
	v_add_f32_e32 v142, 1.0, v142
	v_add_f32_e32 v143, 1.0, v143
	v_rcp_f32_e32 v142, v142
	v_rcp_f32_e32 v143, v143
	s_nop 0
	v_pk_mul_f32 v[138:139], v[138:139], v[142:143]
	s_nop 0
	v_pk_mul_f32 v[138:139], v[130:131], v[138:139]
	v_pk_fma_f32 v[130:131], v[140:141], v[168:169], v[38:39] op_sel_hi:[1,0,1]
	s_nop 0
	v_mul_f32_e32 v140, 0xbfb8aa3b, v130
	v_mul_f32_e32 v141, 0xbfb8aa3b, v131
	v_exp_f32_e32 v140, v140
	v_exp_f32_e32 v141, v141
	v_add_f32_e32 v140, 1.0, v140
	v_add_f32_e32 v141, 1.0, v141
	v_rcp_f32_e32 v140, v140
	v_rcp_f32_e32 v141, v141
	s_nop 0
	v_pk_mul_f32 v[130:131], v[130:131], v[140:141]
	s_nop 0
	v_pk_mul_f32 v[140:141], v[132:133], v[130:131]
	v_cvt_pk_bf16_f32 v130, v134, v135
	v_mov_b64_e32 v[134:135], s[2:3]
	v_cvt_pk_bf16_f32 v131, v136, v137
	v_cvt_pk_bf16_f32 v132, v138, v139
	v_mad_i64_i32 v[138:139], s[4:5], v156, s12, v[134:135]
	v_lshlrev_b64 v[136:137], 1, v[160:161]
	v_cvt_pk_bf16_f32 v133, v140, v141
	v_lshl_add_u64 v[138:139], v[138:139], 0, v[136:137]
	global_store_dwordx4 v[138:139], v[130:133], off
	s_nop 1
	v_or_b32_e32 v130, 16, v156
	v_fmamk_f32 v131, v186, 0x3a800000, v227
	s_nop 0
	v_rsq_f32_e32 v131, v131
	s_nop 0
	v_mov_b32_e32 v132, v131
	v_pk_fma_f32 v[124:125], v[124:125], v[132:133], v[44:45] op_sel_hi:[1,0,1]
	v_pk_fma_f32 v[116:117], v[116:117], v[132:133], v[40:41] op_sel_hi:[1,0,1]
	v_mul_f32_e32 v131, 0xbfb8aa3b, v124
	v_exp_f32_e32 v131, v131
	v_pk_fma_f32 v[118:119], v[118:119], v[132:133], v[42:43] op_sel_hi:[1,0,1]
	v_pk_fma_f32 v[120:121], v[120:121], v[132:133], v[36:37] op_sel_hi:[1,0,1]
	v_pk_fma_f32 v[112:113], v[112:113], v[132:133], v[32:33] op_sel_hi:[1,0,1]
	v_add_f32_e32 v131, 1.0, v131
	v_rcp_f32_e32 v138, v131
	v_mul_f32_e32 v131, 0xbfb8aa3b, v125
	v_exp_f32_e32 v131, v131
	v_pk_fma_f32 v[114:115], v[114:115], v[132:133], v[34:35] op_sel_hi:[1,0,1]
	v_add_f32_e32 v131, 1.0, v131
	v_rcp_f32_e32 v139, v131
	s_nop 0
	v_pk_mul_f32 v[124:125], v[124:125], v[138:139]
	s_nop 0
	v_pk_mul_f32 v[116:117], v[116:117], v[124:125]
	v_pk_fma_f32 v[124:125], v[126:127], v[132:133], v[46:47] op_sel_hi:[1,0,1]
	s_nop 0
	v_mul_f32_e32 v126, 0xbfb8aa3b, v124
	v_mul_f32_e32 v127, 0xbfb8aa3b, v125
	v_exp_f32_e32 v126, v126
	v_exp_f32_e32 v127, v127
	v_add_f32_e32 v126, 1.0, v126
	v_add_f32_e32 v127, 1.0, v127
	v_rcp_f32_e32 v126, v126
	v_rcp_f32_e32 v127, v127
	s_nop 0
	v_pk_mul_f32 v[124:125], v[124:125], v[126:127]
	s_nop 0
	v_pk_mul_f32 v[118:119], v[118:119], v[124:125]
	v_mul_f32_e32 v124, 0xbfb8aa3b, v120
	v_mul_f32_e32 v125, 0xbfb8aa3b, v121
	v_exp_f32_e32 v124, v124
	v_exp_f32_e32 v125, v125
	v_add_f32_e32 v124, 1.0, v124
	v_add_f32_e32 v125, 1.0, v125
	v_rcp_f32_e32 v124, v124
	v_rcp_f32_e32 v125, v125
	s_nop 0
	v_pk_mul_f32 v[120:121], v[120:121], v[124:125]
; __device__ __forceinline__ unsigned pk_bf16(float lo, float hi) { f32x2 v = {lo, hi}; bf16x2_t b = __builtin_convertvector(v, bf16x2_t); return __builtin_bit_cast(unsigned, b); }
;     __device__ __forceinline__ void operator()(const f32x4 (&acc)[2][2][4][2], const Unit& u, int wr, int wc, int fr, int fq) const {
;     ...
;             for (int m = 0; m < 4; ++m) {
;                 float o[8]; const float rv = rsqrtf(rowss[row0 + ai * HALF + m * 16] * (1.0f / 1024.0f) + 1e-6f);
; #pragma unroll
;                 for (int n = 0; n < 2; ++n)
; #pragma unroll
;                     for (int j = 0; j < 4; ++j) { const float g = acc[ai][0][m][n][j] * rv + bz[0][n][j], up = acc[ai][1][m][n][j] * rv + bz[1][n][j];
;                         o[4 * n + j] = g * __builtin_amdgcn_rcpf(1.0f + __expf(-g)) * up; }
;                 u32x4 w; w.x = pk_bf16(o[0], o[1]); w.y = pk_bf16(o[2], o[3]); w.z = pk_bf16(o[4], o[5]); w.w = pk_bf16(o[6], o[7]);
;                 *(u32x4*)(act + (size_t)(row0 + ai * HALF + m * 16) * 2816 + col0) = w;
	s_nop 0
	v_pk_mul_f32 v[120:121], v[112:113], v[120:121]
	v_pk_fma_f32 v[112:113], v[122:123], v[132:133], v[38:39] op_sel_hi:[1,0,1]
	s_nop 0
	v_mul_f32_e32 v122, 0xbfb8aa3b, v112
	v_mul_f32_e32 v123, 0xbfb8aa3b, v113
	v_exp_f32_e32 v122, v122
	v_exp_f32_e32 v123, v123
	v_add_f32_e32 v122, 1.0, v122
	v_add_f32_e32 v123, 1.0, v123
	v_rcp_f32_e32 v122, v122
	v_rcp_f32_e32 v123, v123
	s_nop 0
	v_pk_mul_f32 v[112:113], v[112:113], v[122:123]
	s_nop 0
	v_pk_mul_f32 v[122:123], v[114:115], v[112:113]
	v_cvt_pk_bf16_f32 v112, v116, v117
	v_mad_i64_i32 v[116:117], s[4:5], v130, s12, v[134:135]
	v_cvt_pk_bf16_f32 v113, v118, v119
	v_cvt_pk_bf16_f32 v114, v120, v121
	v_cvt_pk_bf16_f32 v115, v122, v123
	v_lshl_add_u64 v[116:117], v[116:117], 0, v[136:137]
	global_store_dwordx4 v[116:117], v[112:115], off
	s_nop 1
	v_or_b32_e32 v112, 32, v156
	v_fmamk_f32 v113, v187, 0x3a800000, v227
	s_nop 0
	v_rsq_f32_e32 v113, v113
	s_nop 0
	v_mov_b32_e32 v114, v113
	v_pk_fma_f32 v[108:109], v[108:109], v[114:115], v[44:45] op_sel_hi:[1,0,1]
	v_pk_fma_f32 v[100:101], v[100:101], v[114:115], v[40:41] op_sel_hi:[1,0,1]
	v_mul_f32_e32 v113, 0xbfb8aa3b, v108
	v_exp_f32_e32 v113, v113
	v_pk_fma_f32 v[102:103], v[102:103], v[114:115], v[42:43] op_sel_hi:[1,0,1]
	v_pk_fma_f32 v[104:105], v[104:105], v[114:115], v[36:37] op_sel_hi:[1,0,1]
	v_pk_fma_f32 v[96:97], v[96:97], v[114:115], v[32:33] op_sel_hi:[1,0,1]
	v_add_f32_e32 v113, 1.0, v113
	v_rcp_f32_e32 v116, v113
	v_mul_f32_e32 v113, 0xbfb8aa3b, v109
	v_exp_f32_e32 v113, v113
	v_pk_fma_f32 v[98:99], v[98:99], v[114:115], v[34:35] op_sel_hi:[1,0,1]
	v_add_f32_e32 v113, 1.0, v113
	v_rcp_f32_e32 v117, v113
	s_nop 0
	v_pk_mul_f32 v[108:109], v[108:109], v[116:117]
	s_nop 0
	v_pk_mul_f32 v[100:101], v[100:101], v[108:109]
	v_pk_fma_f32 v[108:109], v[110:111], v[114:115], v[46:47] op_sel_hi:[1,0,1]
	s_nop 0
	v_mul_f32_e32 v110, 0xbfb8aa3b, v108
	v_mul_f32_e32 v111, 0xbfb8aa3b, v109
	v_exp_f32_e32 v110, v110
	v_exp_f32_e32 v111, v111
	v_add_f32_e32 v110, 1.0, v110
	v_add_f32_e32 v111, 1.0, v111
	v_rcp_f32_e32 v110, v110
	v_rcp_f32_e32 v111, v111
	s_nop 0
	v_pk_mul_f32 v[108:109], v[108:109], v[110:111]
	s_nop 0
	v_pk_mul_f32 v[102:103], v[102:103], v[108:109]
	v_mul_f32_e32 v108, 0xbfb8aa3b, v104
	v_mul_f32_e32 v109, 0xbfb8aa3b, v105
	v_exp_f32_e32 v108, v108
	v_exp_f32_e32 v109, v109
	v_add_f32_e32 v108, 1.0, v108
	v_add_f32_e32 v109, 1.0, v109
	v_rcp_f32_e32 v108, v108
	v_rcp_f32_e32 v109, v109
	s_nop 0
	v_pk_mul_f32 v[104:105], v[104:105], v[108:109]
	s_nop 0
	v_pk_mul_f32 v[104:105], v[96:97], v[104:105]
	v_pk_fma_f32 v[96:97], v[106:107], v[114:115], v[38:39] op_sel_hi:[1,0,1]
	s_nop 0
	v_mul_f32_e32 v106, 0xbfb8aa3b, v96
	v_mul_f32_e32 v107, 0xbfb8aa3b, v97
	v_exp_f32_e32 v106, v106
	v_exp_f32_e32 v107, v107
	v_add_f32_e32 v106, 1.0, v106
	v_add_f32_e32 v107, 1.0, v107
	v_rcp_f32_e32 v106, v106
	v_rcp_f32_e32 v107, v107
	s_nop 0
	v_pk_mul_f32 v[96:97], v[96:97], v[106:107]
	s_nop 0
	v_pk_mul_f32 v[106:107], v[98:99], v[96:97]
	v_cvt_pk_bf16_f32 v96, v100, v101
	v_mad_i64_i32 v[100:101], s[4:5], v112, s12, v[134:135]
	v_cvt_pk_bf16_f32 v97, v102, v103
	v_cvt_pk_bf16_f32 v98, v104, v105
	v_cvt_pk_bf16_f32 v99, v106, v107
	v_lshl_add_u64 v[100:101], v[100:101], 0, v[136:137]
	global_store_dwordx4 v[100:101], v[96:99], off
	s_nop 1
	v_or_b32_e32 v96, 48, v156
	v_fmamk_f32 v97, v188, 0x3a800000, v227
	s_nop 0
	v_rsq_f32_e32 v97, v97
	s_nop 0
	v_mov_b32_e32 v98, v97
	v_pk_fma_f32 v[92:93], v[92:93], v[98:99], v[44:45] op_sel_hi:[1,0,1]
	v_pk_fma_f32 v[84:85], v[84:85], v[98:99], v[40:41] op_sel_hi:[1,0,1]
	v_mul_f32_e32 v97, 0xbfb8aa3b, v92
	v_exp_f32_e32 v97, v97
	v_pk_fma_f32 v[86:87], v[86:87], v[98:99], v[42:43] op_sel_hi:[1,0,1]
	v_pk_fma_f32 v[88:89], v[88:89], v[98:99], v[36:37] op_sel_hi:[1,0,1]
	v_pk_fma_f32 v[80:81], v[80:81], v[98:99], v[32:33] op_sel_hi:[1,0,1]
	v_add_f32_e32 v97, 1.0, v97
	v_rcp_f32_e32 v100, v97
	v_mul_f32_e32 v97, 0xbfb8aa3b, v93
	v_exp_f32_e32 v97, v97
	v_pk_fma_f32 v[82:83], v[82:83], v[98:99], v[34:35] op_sel_hi:[1,0,1]
	v_add_f32_e32 v97, 1.0, v97
	v_rcp_f32_e32 v101, v97
	s_nop 0
	v_pk_mul_f32 v[92:93], v[92:93], v[100:101]
	s_nop 0
	v_pk_mul_f32 v[84:85], v[84:85], v[92:93]
	v_pk_fma_f32 v[92:93], v[94:95], v[98:99], v[46:47] op_sel_hi:[1,0,1]
	s_nop 0
	v_mul_f32_e32 v94, 0xbfb8aa3b, v92
	v_mul_f32_e32 v95, 0xbfb8aa3b, v93
	v_exp_f32_e32 v94, v94
	v_exp_f32_e32 v95, v95
	v_add_f32_e32 v94, 1.0, v94
	v_add_f32_e32 v95, 1.0, v95
	v_rcp_f32_e32 v94, v94
	v_rcp_f32_e32 v95, v95
	s_nop 0
	v_pk_mul_f32 v[92:93], v[92:93], v[94:95]
	s_nop 0
	v_pk_mul_f32 v[86:87], v[86:87], v[92:93]
	v_mul_f32_e32 v92, 0xbfb8aa3b, v88
	v_mul_f32_e32 v93, 0xbfb8aa3b, v89
	v_exp_f32_e32 v92, v92
	v_exp_f32_e32 v93, v93
	v_add_f32_e32 v92, 1.0, v92
	v_add_f32_e32 v93, 1.0, v93
	v_rcp_f32_e32 v92, v92
	v_rcp_f32_e32 v93, v93
	s_nop 0
	v_pk_mul_f32 v[88:89], v[88:89], v[92:93]
	s_nop 0
	v_pk_mul_f32 v[88:89], v[80:81], v[88:89]
	v_pk_fma_f32 v[80:81], v[90:91], v[98:99], v[38:39] op_sel_hi:[1,0,1]
	s_nop 0
	v_mul_f32_e32 v90, 0xbfb8aa3b, v80
	v_mul_f32_e32 v91, 0xbfb8aa3b, v81
	v_exp_f32_e32 v90, v90
	v_exp_f32_e32 v91, v91
	v_add_f32_e32 v90, 1.0, v90
	v_add_f32_e32 v91, 1.0, v91
	v_rcp_f32_e32 v90, v90
	v_rcp_f32_e32 v91, v91
	s_nop 0
	v_pk_mul_f32 v[80:81], v[80:81], v[90:91]
	s_nop 0
	v_pk_mul_f32 v[90:91], v[82:83], v[80:81]
	v_cvt_pk_bf16_f32 v80, v84, v85
	v_mad_i64_i32 v[84:85], s[4:5], v96, s12, v[134:135]
	v_cvt_pk_bf16_f32 v81, v86, v87
	v_cvt_pk_bf16_f32 v82, v88, v89
	v_cvt_pk_bf16_f32 v83, v90, v91
	v_lshl_add_u64 v[84:85], v[84:85], 0, v[136:137]
	global_store_dwordx4 v[84:85], v[80:83], off
; __device__ __forceinline__ unsigned pk_bf16(float lo, float hi) { f32x2 v = {lo, hi}; bf16x2_t b = __builtin_convertvector(v, bf16x2_t); return __builtin_bit_cast(unsigned, b); }
;     __device__ __forceinline__ void operator()(const f32x4 (&acc)[2][2][4][2], const Unit& u, int wr, int wc, int fr, int fq) const {
;     ...
;             for (int m = 0; m < 4; ++m) {
;                 float o[8]; const float rv = rsqrtf(rowss[row0 + ai * HALF + m * 16] * (1.0f / 1024.0f) + 1e-6f);
; #pragma unroll
;                 for (int n = 0; n < 2; ++n)
; #pragma unroll
;                     for (int j = 0; j < 4; ++j) { const float g = acc[ai][0][m][n][j] * rv + bz[0][n][j], up = acc[ai][1][m][n][j] * rv + bz[1][n][j];
;                         o[4 * n + j] = g * __builtin_amdgcn_rcpf(1.0f + __expf(-g)) * up; }
;                 u32x4 w; w.x = pk_bf16(o[0], o[1]); w.y = pk_bf16(o[2], o[3]); w.z = pk_bf16(o[4], o[5]); w.w = pk_bf16(o[6], o[7]);
;                 *(u32x4*)(act + (size_t)(row0 + ai * HALF + m * 16) * 2816 + col0) = w;
	s_nop 0
	s_nop 0
	v_add_u32_e32 v81, 0x80, v156
	v_fmamk_f32 v80, v189, 0x3a800000, v227
	s_nop 0
	v_rsq_f32_e32 v80, v80
	s_nop 0
	v_pk_fma_f32 v[76:77], v[76:77], v[80:81], v[44:45] op_sel_hi:[1,0,1]
	v_pk_fma_f32 v[68:69], v[68:69], v[80:81], v[40:41] op_sel_hi:[1,0,1]
	v_mul_f32_e32 v82, 0xbfb8aa3b, v76
	v_mul_f32_e32 v83, 0xbfb8aa3b, v77
	v_exp_f32_e32 v82, v82
	v_exp_f32_e32 v83, v83
	v_pk_fma_f32 v[70:71], v[70:71], v[80:81], v[42:43] op_sel_hi:[1,0,1]
	v_pk_fma_f32 v[72:73], v[72:73], v[80:81], v[36:37] op_sel_hi:[1,0,1]
	v_add_f32_e32 v82, 1.0, v82
	v_add_f32_e32 v83, 1.0, v83
	v_rcp_f32_e32 v82, v82
	v_rcp_f32_e32 v83, v83
	v_pk_fma_f32 v[64:65], v[64:65], v[80:81], v[32:33] op_sel_hi:[1,0,1]
	v_pk_fma_f32 v[66:67], v[66:67], v[80:81], v[34:35] op_sel_hi:[1,0,1]
	v_pk_mul_f32 v[76:77], v[76:77], v[82:83]
	s_nop 0
	v_pk_mul_f32 v[68:69], v[68:69], v[76:77]
	v_pk_fma_f32 v[76:77], v[78:79], v[80:81], v[46:47] op_sel_hi:[1,0,1]
	s_nop 0
	v_mul_f32_e32 v78, 0xbfb8aa3b, v76
	v_mul_f32_e32 v79, 0xbfb8aa3b, v77
	v_exp_f32_e32 v78, v78
	v_exp_f32_e32 v79, v79
	v_add_f32_e32 v78, 1.0, v78
	v_add_f32_e32 v79, 1.0, v79
	v_rcp_f32_e32 v78, v78
	v_rcp_f32_e32 v79, v79
	s_nop 0
	v_pk_mul_f32 v[76:77], v[76:77], v[78:79]
	s_nop 0
	v_pk_mul_f32 v[70:71], v[70:71], v[76:77]
	v_mul_f32_e32 v76, 0xbfb8aa3b, v72
	v_mul_f32_e32 v77, 0xbfb8aa3b, v73
	v_exp_f32_e32 v76, v76
	v_exp_f32_e32 v77, v77
	v_add_f32_e32 v76, 1.0, v76
	v_add_f32_e32 v77, 1.0, v77
	v_rcp_f32_e32 v76, v76
	v_rcp_f32_e32 v77, v77
	s_nop 0
	v_pk_mul_f32 v[72:73], v[72:73], v[76:77]
	s_nop 0
	v_pk_mul_f32 v[72:73], v[64:65], v[72:73]
	v_pk_fma_f32 v[64:65], v[74:75], v[80:81], v[38:39] op_sel_hi:[1,0,1]
	s_nop 0
	v_mul_f32_e32 v74, 0xbfb8aa3b, v64
	v_mul_f32_e32 v75, 0xbfb8aa3b, v65
	v_exp_f32_e32 v74, v74
	v_exp_f32_e32 v75, v75
	v_add_f32_e32 v74, 1.0, v74
	v_add_f32_e32 v75, 1.0, v75
	v_rcp_f32_e32 v74, v74
	v_rcp_f32_e32 v75, v75
	s_nop 0
	v_pk_mul_f32 v[64:65], v[64:65], v[74:75]
	s_nop 0
	v_pk_mul_f32 v[74:75], v[66:67], v[64:65]
	v_cvt_pk_bf16_f32 v64, v68, v69
	v_mad_i64_i32 v[68:69], s[4:5], v81, s12, v[134:135]
	v_cvt_pk_bf16_f32 v65, v70, v71
	v_cvt_pk_bf16_f32 v66, v72, v73
	v_cvt_pk_bf16_f32 v67, v74, v75
	v_lshl_add_u64 v[68:69], v[68:69], 0, v[136:137]
	global_store_dwordx4 v[68:69], v[64:67], off
	s_nop 0
	s_nop 0
	v_add_u32_e32 v65, 0x90, v156
	v_fmamk_f32 v64, v190, 0x3a800000, v227
	s_nop 0
	v_rsq_f32_e32 v64, v64
	s_nop 0
	v_pk_fma_f32 v[60:61], v[60:61], v[64:65], v[44:45] op_sel_hi:[1,0,1]
	v_pk_fma_f32 v[52:53], v[52:53], v[64:65], v[40:41] op_sel_hi:[1,0,1]
	v_mul_f32_e32 v66, 0xbfb8aa3b, v60
	v_mul_f32_e32 v67, 0xbfb8aa3b, v61
	v_exp_f32_e32 v66, v66
	v_exp_f32_e32 v67, v67
	v_pk_fma_f32 v[54:55], v[54:55], v[64:65], v[42:43] op_sel_hi:[1,0,1]
	v_pk_fma_f32 v[56:57], v[56:57], v[64:65], v[36:37] op_sel_hi:[1,0,1]
	v_add_f32_e32 v66, 1.0, v66
	v_add_f32_e32 v67, 1.0, v67
	v_rcp_f32_e32 v66, v66
	v_rcp_f32_e32 v67, v67
	v_pk_fma_f32 v[48:49], v[48:49], v[64:65], v[32:33] op_sel_hi:[1,0,1]
	v_pk_fma_f32 v[50:51], v[50:51], v[64:65], v[34:35] op_sel_hi:[1,0,1]
	v_pk_mul_f32 v[60:61], v[60:61], v[66:67]
	s_nop 0
	v_pk_mul_f32 v[52:53], v[52:53], v[60:61]
	v_pk_fma_f32 v[60:61], v[62:63], v[64:65], v[46:47] op_sel_hi:[1,0,1]
	s_nop 0
	v_mul_f32_e32 v62, 0xbfb8aa3b, v60
	v_mul_f32_e32 v63, 0xbfb8aa3b, v61
	v_exp_f32_e32 v62, v62
	v_exp_f32_e32 v63, v63
	v_add_f32_e32 v62, 1.0, v62
	v_add_f32_e32 v63, 1.0, v63
	v_rcp_f32_e32 v62, v62
	v_rcp_f32_e32 v63, v63
	s_nop 0
	v_pk_mul_f32 v[60:61], v[60:61], v[62:63]
	s_nop 0
	v_pk_mul_f32 v[54:55], v[54:55], v[60:61]
	v_mul_f32_e32 v60, 0xbfb8aa3b, v56
	v_mul_f32_e32 v61, 0xbfb8aa3b, v57
	v_exp_f32_e32 v60, v60
	v_exp_f32_e32 v61, v61
	v_add_f32_e32 v60, 1.0, v60
	v_add_f32_e32 v61, 1.0, v61
	v_rcp_f32_e32 v60, v60
	v_rcp_f32_e32 v61, v61
	s_nop 0
	v_pk_mul_f32 v[56:57], v[56:57], v[60:61]
	s_nop 0
	v_pk_mul_f32 v[56:57], v[48:49], v[56:57]
	v_pk_fma_f32 v[48:49], v[58:59], v[64:65], v[38:39] op_sel_hi:[1,0,1]
	s_nop 0
	v_mul_f32_e32 v58, 0xbfb8aa3b, v48
	v_mul_f32_e32 v59, 0xbfb8aa3b, v49
	v_exp_f32_e32 v58, v58
	v_exp_f32_e32 v59, v59
	v_add_f32_e32 v58, 1.0, v58
	v_add_f32_e32 v59, 1.0, v59
	v_rcp_f32_e32 v58, v58
	v_rcp_f32_e32 v59, v59
	s_nop 0
	v_pk_mul_f32 v[48:49], v[48:49], v[58:59]
	s_nop 0
	v_pk_mul_f32 v[58:59], v[50:51], v[48:49]
	v_cvt_pk_bf16_f32 v48, v52, v53
	v_mad_i64_i32 v[52:53], s[4:5], v65, s12, v[134:135]
	v_cvt_pk_bf16_f32 v49, v54, v55
	v_cvt_pk_bf16_f32 v50, v56, v57
	v_cvt_pk_bf16_f32 v51, v58, v59
	v_lshl_add_u64 v[52:53], v[52:53], 0, v[136:137]
	global_store_dwordx4 v[52:53], v[48:51], off
	s_nop 0
	s_nop 0
	v_add_u32_e32 v49, 0xa0, v156
; __device__ __forceinline__ unsigned pk_bf16(float lo, float hi) { f32x2 v = {lo, hi}; bf16x2_t b = __builtin_convertvector(v, bf16x2_t); return __builtin_bit_cast(unsigned, b); }
; #define PG8_BAR __builtin_amdgcn_s_barrier()
;     __device__ __forceinline__ void operator()(const f32x4 (&acc)[2][2][4][2], const Unit& u, int wr, int wc, int fr, int fq) const {
;     ...
; #pragma unroll
;         for (int ai = 0; ai < 2; ++ai)
; #pragma unroll
;             for (int m = 0; m < 4; ++m) {
;                 float o[8]; const float rv = rsqrtf(rowss[row0 + ai * HALF + m * 16] * (1.0f / 1024.0f) + 1e-6f);
; #pragma unroll
;                 for (int n = 0; n < 2; ++n)
; #pragma unroll
;                     for (int j = 0; j < 4; ++j) { const float g = acc[ai][0][m][n][j] * rv + bz[0][n][j], up = acc[ai][1][m][n][j] * rv + bz[1][n][j];
;                         o[4 * n + j] = g * __builtin_amdgcn_rcpf(1.0f + __expf(-g)) * up; }
;                 u32x4 w; w.x = pk_bf16(o[0], o[1]); w.y = pk_bf16(o[2], o[3]); w.z = pk_bf16(o[4], o[5]); w.w = pk_bf16(o[6], o[7]);
;                 *(u32x4*)(act + (size_t)(row0 + ai * HALF + m * 16) * 2816 + col0) = w;
;             }
; template <class Epi, class Sched, bool ALIGN_EPI = false, bool SP2 = false, bool F16 = false>
; __device__ __forceinline__ void gemm_phase(PG8_LAS unsigned char* lds, const Gemm g, const Sched& S, const Epi& E) {
;     ...
;         if (!has_next) break;
; #pragma unroll
;         for (int a = 0; a < 2; ++a)
; #pragma unroll
;             for (int b = 0; b < 2; ++b)
; #pragma unroll
;                 for (int m = 0; m < 4; ++m)
; #pragma unroll
;                     for (int n = 0; n < 2; ++n) acc[a][b][m][n] = (f32x4){0.f, 0.f, 0.f, 0.f};
;         cur = nxt; cA = nA; cB = nB; ++ui;
;         if constexpr (ALIGN_EPI) { if (wr == 1) PG8_BAR; }
	v_fmamk_f32 v48, v191, 0x3a800000, v227
	s_nop 0
	v_rsq_f32_e32 v48, v48
	s_nop 0
	v_pk_fma_f32 v[28:29], v[28:29], v[48:49], v[44:45] op_sel_hi:[1,0,1]
	v_pk_fma_f32 v[20:21], v[20:21], v[48:49], v[40:41] op_sel_hi:[1,0,1]
	v_mul_f32_e32 v50, 0xbfb8aa3b, v28
	v_mul_f32_e32 v51, 0xbfb8aa3b, v29
	v_exp_f32_e32 v50, v50
	v_exp_f32_e32 v51, v51
	v_pk_fma_f32 v[22:23], v[22:23], v[48:49], v[42:43] op_sel_hi:[1,0,1]
	v_pk_fma_f32 v[24:25], v[24:25], v[48:49], v[36:37] op_sel_hi:[1,0,1]
	v_add_f32_e32 v50, 1.0, v50
	v_add_f32_e32 v51, 1.0, v51
	v_rcp_f32_e32 v50, v50
	v_rcp_f32_e32 v51, v51
	v_pk_fma_f32 v[16:17], v[16:17], v[48:49], v[32:33] op_sel_hi:[1,0,1]
	v_pk_fma_f32 v[18:19], v[18:19], v[48:49], v[34:35] op_sel_hi:[1,0,1]
	v_pk_mul_f32 v[28:29], v[28:29], v[50:51]
	s_nop 0
	v_pk_mul_f32 v[20:21], v[20:21], v[28:29]
	v_pk_fma_f32 v[28:29], v[30:31], v[48:49], v[46:47] op_sel_hi:[1,0,1]
	s_nop 0
	v_mul_f32_e32 v30, 0xbfb8aa3b, v28
	v_mul_f32_e32 v31, 0xbfb8aa3b, v29
	v_exp_f32_e32 v30, v30
	v_exp_f32_e32 v31, v31
	v_add_f32_e32 v30, 1.0, v30
	v_add_f32_e32 v31, 1.0, v31
	v_rcp_f32_e32 v30, v30
	v_rcp_f32_e32 v31, v31
	s_nop 0
	v_pk_mul_f32 v[28:29], v[28:29], v[30:31]
	s_nop 0
	v_pk_mul_f32 v[22:23], v[22:23], v[28:29]
	v_mul_f32_e32 v28, 0xbfb8aa3b, v24
	v_mul_f32_e32 v29, 0xbfb8aa3b, v25
	v_exp_f32_e32 v28, v28
	v_exp_f32_e32 v29, v29
	v_add_f32_e32 v28, 1.0, v28
	v_add_f32_e32 v29, 1.0, v29
	v_rcp_f32_e32 v28, v28
	v_rcp_f32_e32 v29, v29
	s_nop 0
	v_pk_mul_f32 v[24:25], v[24:25], v[28:29]
	s_nop 0
	v_pk_mul_f32 v[24:25], v[16:17], v[24:25]
	v_pk_fma_f32 v[16:17], v[26:27], v[48:49], v[38:39] op_sel_hi:[1,0,1]
	s_nop 0
	v_mul_f32_e32 v26, 0xbfb8aa3b, v16
	v_mul_f32_e32 v27, 0xbfb8aa3b, v17
	v_exp_f32_e32 v26, v26
	v_exp_f32_e32 v27, v27
	v_add_f32_e32 v26, 1.0, v26
	v_add_f32_e32 v27, 1.0, v27
	v_rcp_f32_e32 v26, v26
	v_rcp_f32_e32 v27, v27
	s_nop 0
	v_pk_mul_f32 v[16:17], v[16:17], v[26:27]
	s_nop 0
	v_pk_mul_f32 v[26:27], v[18:19], v[16:17]
	v_cvt_pk_bf16_f32 v16, v20, v21
	v_mad_i64_i32 v[20:21], s[4:5], v49, s12, v[134:135]
	v_cvt_pk_bf16_f32 v17, v22, v23
	v_cvt_pk_bf16_f32 v18, v24, v25
	v_cvt_pk_bf16_f32 v19, v26, v27
	v_lshl_add_u64 v[20:21], v[20:21], 0, v[136:137]
	global_store_dwordx4 v[20:21], v[16:19], off
	s_nop 0
	s_nop 0
	v_add_u32_e32 v17, 0xb0, v156
	v_fmamk_f32 v16, v192, 0x3a800000, v227
	s_nop 0
	v_rsq_f32_e32 v16, v16
	s_nop 0
	v_pk_fma_f32 v[12:13], v[12:13], v[16:17], v[44:45] op_sel_hi:[1,0,1]
	v_pk_fma_f32 v[4:5], v[4:5], v[16:17], v[40:41] op_sel_hi:[1,0,1]
	v_mul_f32_e32 v18, 0xbfb8aa3b, v12
	v_mul_f32_e32 v19, 0xbfb8aa3b, v13
	v_exp_f32_e32 v18, v18
	v_exp_f32_e32 v19, v19
	v_pk_fma_f32 v[6:7], v[6:7], v[16:17], v[42:43] op_sel_hi:[1,0,1]
	v_pk_fma_f32 v[8:9], v[8:9], v[16:17], v[36:37] op_sel_hi:[1,0,1]
	v_add_f32_e32 v18, 1.0, v18
	v_add_f32_e32 v19, 1.0, v19
	v_rcp_f32_e32 v18, v18
	v_rcp_f32_e32 v19, v19
	v_pk_fma_f32 v[0:1], v[0:1], v[16:17], v[32:33] op_sel_hi:[1,0,1]
	v_pk_fma_f32 v[2:3], v[2:3], v[16:17], v[34:35] op_sel_hi:[1,0,1]
	s_andn2_b64 vcc, exec, s[40:41]
	v_pk_mul_f32 v[12:13], v[12:13], v[18:19]
	s_nop 0
	v_pk_mul_f32 v[4:5], v[4:5], v[12:13]
	v_pk_fma_f32 v[12:13], v[14:15], v[16:17], v[46:47] op_sel_hi:[1,0,1]
	s_nop 0
	v_mul_f32_e32 v14, 0xbfb8aa3b, v12
	v_mul_f32_e32 v15, 0xbfb8aa3b, v13
	v_exp_f32_e32 v14, v14
	v_exp_f32_e32 v15, v15
	v_add_f32_e32 v14, 1.0, v14
	v_add_f32_e32 v15, 1.0, v15
	v_rcp_f32_e32 v14, v14
	v_rcp_f32_e32 v15, v15
	s_nop 0
	v_pk_mul_f32 v[12:13], v[12:13], v[14:15]
	s_nop 0
	v_pk_mul_f32 v[6:7], v[6:7], v[12:13]
	v_mul_f32_e32 v12, 0xbfb8aa3b, v8
	v_mul_f32_e32 v13, 0xbfb8aa3b, v9
	v_exp_f32_e32 v12, v12
	v_exp_f32_e32 v13, v13
	v_add_f32_e32 v12, 1.0, v12
	v_add_f32_e32 v13, 1.0, v13
	v_rcp_f32_e32 v12, v12
	v_rcp_f32_e32 v13, v13
	s_nop 0
	v_pk_mul_f32 v[8:9], v[8:9], v[12:13]
	s_nop 0
	v_pk_mul_f32 v[8:9], v[0:1], v[8:9]
	v_pk_fma_f32 v[0:1], v[10:11], v[16:17], v[38:39] op_sel_hi:[1,0,1]
	s_nop 0
	v_mul_f32_e32 v10, 0xbfb8aa3b, v0
	v_mul_f32_e32 v11, 0xbfb8aa3b, v1
	v_exp_f32_e32 v10, v10
	v_exp_f32_e32 v11, v11
	v_add_f32_e32 v10, 1.0, v10
	v_add_f32_e32 v11, 1.0, v11
	v_rcp_f32_e32 v10, v10
	v_rcp_f32_e32 v11, v11
	s_nop 0
	v_pk_mul_f32 v[0:1], v[0:1], v[10:11]
	s_nop 0
	v_pk_mul_f32 v[10:11], v[2:3], v[0:1]
	v_cvt_pk_bf16_f32 v0, v4, v5
	v_mad_i64_i32 v[4:5], s[4:5], v17, s12, v[134:135]
	v_cvt_pk_bf16_f32 v1, v6, v7
	v_cvt_pk_bf16_f32 v2, v8, v9
	v_cvt_pk_bf16_f32 v3, v10, v11
	v_lshl_add_u64 v[4:5], v[4:5], 0, v[136:137]
	global_store_dwordx4 v[4:5], v[0:3], off
	s_cbranch_vccnz .LBB0_900
	s_andn2_b64 vcc, exec, s[0:1]
	s_cbranch_vccnz .LBB0_899
	s_barrier
	s_branch .LBB0_899
